# local barrier waits a,b: counter load issued before the store drain + s_barrier so the first poll overlaps them
# speedup vs baseline: 1.0024x; 1.0024x over previous
.LBB0_256:
	v_readlane_b32 s0, v255, 13
	v_readlane_b32 s4, v252, 7
	s_add_i32 s10, s0, 2
	v_readlane_b32 s7, v252, 10
	s_cmp_ge_i32 s10, s7
	s_barrier
	v_readlane_b32 s5, v252, 8
	v_readlane_b32 s6, v252, 9
	s_cbranch_scc1 .LBB0_310
	v_readlane_b32 s74, v255, 62
	s_nop 3
	s_cmp_eq_u32 s74, 0
	s_cbranch_scc1 .Lglob_a
	s_mov_b64 s[76:77], exec
	v_readlane_b32 s78, v252, 11
	v_readlane_b32 s79, v252, 12
	v_readlane_b32 s80, v253, 26
	v_readlane_b32 s81, v253, 27
	s_nop 3
	s_add_u32 s80, s80, 0x2300
	s_addc_u32 s81, s81, 0
	s_and_b64 s[78:79], s[76:77], s[78:79]
	s_mov_b64 exec, s[78:79]
	s_nop 1
	global_load_dword v2, v3, s[80:81] sc1
	s_mov_b64 exec, s[76:77]
	s_waitcnt vmcnt(0) lgkmcnt(0)
	s_barrier
	s_mov_b64 s[76:77], exec
	v_readlane_b32 s78, v252, 11
	v_readlane_b32 s79, v252, 12
	s_nop 3
	s_and_b64 s[78:79], s[76:77], s[78:79]
	s_mov_b64 exec, s[78:79]
	s_cbranch_execz .Lloc_done_a
	v_readlane_b32 s80, v253, 26
	v_readlane_b32 s81, v253, 27
	v_readlane_b32 s82, v255, 13
	s_nop 3
	s_add_u32 s80, s80, 0x2300
	s_addc_u32 s81, s81, 0
	s_cmp_lg_u32 s82, 0
	s_cselect_b32 s82, 0x40, 0
	s_add_i32 s82, s82, 32
	s_mov_b32 s84, 0
	s_branch .Lloc_chk_a

.Lloc_chk_a:
	v_readfirstlane_b32 s83, v2
	s_nop 3
	s_cmp_ge_u32 s83, s82
	s_cbranch_scc1 .Lloc_rel_a
	s_add_i32 s84, s84, 1
	s_cmp_gt_u32 s84, 0x40000
	s_cbranch_scc1 .Lloc_rel_a
	s_sleep 1
	s_branch .Lloc_spin_a

.LBB0_397:
	v_readlane_b32 s0, v255, 13
	v_readlane_b32 s4, v252, 7
	s_add_i32 s10, s0, 3
	v_readlane_b32 s7, v252, 10
	s_cmp_lt_i32 s10, s7
	v_readlane_b32 s5, v252, 8
	v_readlane_b32 s6, v252, 9
	s_cbranch_scc0 .LBB0_451
	v_readlane_b32 s74, v255, 62
	s_nop 3
	s_cmp_eq_u32 s74, 0
	s_cbranch_scc1 .Lglob_b
	s_mov_b64 s[76:77], exec
	v_readlane_b32 s78, v252, 11
	v_readlane_b32 s79, v252, 12
	v_readlane_b32 s80, v253, 26
	v_readlane_b32 s81, v253, 27
	s_nop 3
	s_add_u32 s80, s80, 0x2300
	s_addc_u32 s81, s81, 0
	s_and_b64 s[78:79], s[76:77], s[78:79]
	s_mov_b64 exec, s[78:79]
	s_nop 1
	global_load_dword v2, v3, s[80:81] sc1
	s_mov_b64 exec, s[76:77]
	s_waitcnt vmcnt(0) lgkmcnt(0)
	s_barrier
	s_mov_b64 s[76:77], exec
	v_readlane_b32 s78, v252, 11
	v_readlane_b32 s79, v252, 12
	s_nop 3
	s_and_b64 s[78:79], s[76:77], s[78:79]
	s_mov_b64 exec, s[78:79]
	s_cbranch_execz .Lloc_done_b
	v_readlane_b32 s80, v253, 26
	v_readlane_b32 s81, v253, 27
	v_readlane_b32 s82, v255, 13
	s_nop 3
	s_add_u32 s80, s80, 0x2300
	s_addc_u32 s81, s81, 0
	s_cmp_lg_u32 s82, 0
	s_cselect_b32 s82, 0x40, 0
	s_add_i32 s82, s82, 64
	s_mov_b32 s84, 0
	s_branch .Lloc_chk_b
